# streaming (nt) hint on the read-once f32 input loads of phase 0 / phase-1 tail conversion tiles and the activation conversion, so they do not displace reusable data in the caches
# speedup vs baseline: 1.0146x; 1.0146x over previous
.LBB0_74:
	v_readlane_b32 s19, v253, 0
	s_mov_b32 s18, s19
	s_mov_b32 s26, s19
	s_ashr_i32 s27, s26, 31
	s_waitcnt lgkmcnt(1)
	v_mov_b32_e32 v2, v230
	s_lshl_b64 s[18:19], s[26:27], 12
	s_waitcnt lgkmcnt(0)
	v_ashrrev_i32_e32 v3, 31, v2
	v_lshl_add_u64 v[0:1], v[2:3], 3, s[18:19]
	s_mov_b64 s[18:19], 0x1000000
	v_cmp_gt_u64_e32 vcc, s[18:19], v[0:1]
	v_lshlrev_b64 v[4:5], 5, v[2:3]
	s_and_saveexec_b64 s[28:29], vcc
	s_cbranch_execz .LBB0_77
	s_lshl_b64 s[18:19], s[26:27], 14
	v_readlane_b32 s30, v254, 46
	s_add_u32 s18, s30, s18
	v_readlane_b32 s30, v254, 62
	s_addc_u32 s19, s30, s19
	v_lshl_add_u64 v[16:17], s[18:19], 0, v[4:5]
	s_lshl_b64 s[18:19], s[26:27], 13
	v_readlane_b32 s30, v255, 0
	s_add_u32 s18, s30, s18
	v_readlane_b32 s30, v255, 2
	s_addc_u32 s19, s30, s19
	v_lshl_add_u64 v[18:19], v[2:3], 4, s[18:19]
	s_mov_b64 s[18:19], 0
	v_mov_b64_e32 v[20:21], v[0:1]
	s_cmp_lg_u32 s22, 0x100000
	s_cbranch_scc1 .LBB0_76
	s_cmp_lg_u32 s23, 0
	s_cbranch_scc1 .LBB0_76
	global_load_dwordx4 v[24:27], v[16:17], off offset:-16 nt
	global_load_dwordx4 v[28:31], v[16:17], off nt
	v_lshl_add_u64 v[16:17], v[16:17], 0, s[90:91]
	global_load_dwordx4 v[138:141], v[16:17], off offset:-16 nt
	global_load_dwordx4 v[142:145], v[16:17], off nt
	v_lshl_add_u64 v[16:17], v[16:17], 0, s[90:91]
	global_load_dwordx4 v[146:149], v[16:17], off offset:-16 nt
	global_load_dwordx4 v[150:153], v[16:17], off nt
	v_lshl_add_u64 v[16:17], v[16:17], 0, s[90:91]
	global_load_dwordx4 v[154:157], v[16:17], off offset:-16 nt
	global_load_dwordx4 v[158:161], v[16:17], off nt
	v_lshl_add_u64 v[16:17], v[16:17], 0, s[90:91]
	global_load_dwordx4 v[162:165], v[16:17], off offset:-16 nt
	global_load_dwordx4 v[194:197], v[16:17], off nt
	v_lshl_add_u64 v[16:17], v[16:17], 0, s[90:91]
	global_load_dwordx4 v[198:201], v[16:17], off offset:-16 nt
	global_load_dwordx4 v[202:205], v[16:17], off nt
	v_lshl_add_u64 v[16:17], v[16:17], 0, s[90:91]
	global_load_dwordx4 v[206:209], v[16:17], off offset:-16 nt
	global_load_dwordx4 v[210:213], v[16:17], off nt
	v_lshl_add_u64 v[16:17], v[16:17], 0, s[90:91]
	global_load_dwordx4 v[110:113], v[16:17], off offset:-16 nt
	global_load_dwordx4 v[114:117], v[16:17], off nt
	v_lshl_add_u64 v[16:17], v[16:17], 0, s[90:91]
	s_waitcnt vmcnt(14)
	v_cvt_pk_bf16_f32 v24, v24, v25
	v_cvt_pk_bf16_f32 v25, v26, v27
	v_cvt_pk_bf16_f32 v26, v28, v29
	v_cvt_pk_bf16_f32 v27, v30, v31
	global_store_dwordx4 v[18:19], v[24:27], off
	v_lshl_add_u64 v[18:19], v[18:19], 0, s[92:93]
	s_nop 0
	global_load_dwordx4 v[24:27], v[16:17], off offset:-16 nt
	global_load_dwordx4 v[28:31], v[16:17], off nt
	v_lshl_add_u64 v[16:17], v[16:17], 0, s[90:91]
	s_waitcnt vmcnt(15)
	v_cvt_pk_bf16_f32 v138, v138, v139
	v_cvt_pk_bf16_f32 v139, v140, v141
	v_cvt_pk_bf16_f32 v140, v142, v143
	v_cvt_pk_bf16_f32 v141, v144, v145
	global_store_dwordx4 v[18:19], v[138:141], off
	v_lshl_add_u64 v[18:19], v[18:19], 0, s[92:93]
	s_nop 0
	global_load_dwordx4 v[138:141], v[16:17], off offset:-16 nt
	global_load_dwordx4 v[142:145], v[16:17], off nt
	v_lshl_add_u64 v[16:17], v[16:17], 0, s[90:91]
	s_waitcnt vmcnt(16)
	v_cvt_pk_bf16_f32 v146, v146, v147
	v_cvt_pk_bf16_f32 v147, v148, v149
	v_cvt_pk_bf16_f32 v148, v150, v151
	v_cvt_pk_bf16_f32 v149, v152, v153
	global_store_dwordx4 v[18:19], v[146:149], off
	v_lshl_add_u64 v[18:19], v[18:19], 0, s[92:93]
	s_nop 0
	global_load_dwordx4 v[146:149], v[16:17], off offset:-16 nt
	global_load_dwordx4 v[150:153], v[16:17], off nt
	v_lshl_add_u64 v[16:17], v[16:17], 0, s[90:91]
	s_waitcnt vmcnt(17)
	v_cvt_pk_bf16_f32 v154, v154, v155
	v_cvt_pk_bf16_f32 v155, v156, v157
	v_cvt_pk_bf16_f32 v156, v158, v159
	v_cvt_pk_bf16_f32 v157, v160, v161
	global_store_dwordx4 v[18:19], v[154:157], off
	v_lshl_add_u64 v[18:19], v[18:19], 0, s[92:93]
	s_nop 0
	global_load_dwordx4 v[154:157], v[16:17], off offset:-16 nt
	global_load_dwordx4 v[158:161], v[16:17], off nt
	v_lshl_add_u64 v[16:17], v[16:17], 0, s[90:91]
	s_waitcnt vmcnt(18)
	v_cvt_pk_bf16_f32 v162, v162, v163
	v_cvt_pk_bf16_f32 v163, v164, v165
	v_cvt_pk_bf16_f32 v164, v194, v195
	v_cvt_pk_bf16_f32 v165, v196, v197
	global_store_dwordx4 v[18:19], v[162:165], off
	v_lshl_add_u64 v[18:19], v[18:19], 0, s[92:93]
	s_nop 0
	global_load_dwordx4 v[162:165], v[16:17], off offset:-16 nt
	global_load_dwordx4 v[194:197], v[16:17], off nt
	v_lshl_add_u64 v[16:17], v[16:17], 0, s[90:91]
	s_waitcnt vmcnt(19)
	v_cvt_pk_bf16_f32 v198, v198, v199
	v_cvt_pk_bf16_f32 v199, v200, v201
	v_cvt_pk_bf16_f32 v200, v202, v203
	v_cvt_pk_bf16_f32 v201, v204, v205
	global_store_dwordx4 v[18:19], v[198:201], off
	v_lshl_add_u64 v[18:19], v[18:19], 0, s[92:93]
	s_nop 0
	global_load_dwordx4 v[198:201], v[16:17], off offset:-16 nt
	global_load_dwordx4 v[202:205], v[16:17], off nt
	v_lshl_add_u64 v[16:17], v[16:17], 0, s[90:91]
	s_waitcnt vmcnt(20)
	v_cvt_pk_bf16_f32 v206, v206, v207
	v_cvt_pk_bf16_f32 v207, v208, v209
	v_cvt_pk_bf16_f32 v208, v210, v211
	v_cvt_pk_bf16_f32 v209, v212, v213
	global_store_dwordx4 v[18:19], v[206:209], off
	v_lshl_add_u64 v[18:19], v[18:19], 0, s[92:93]
	s_nop 0
	global_load_dwordx4 v[206:209], v[16:17], off offset:-16 nt
	global_load_dwordx4 v[210:213], v[16:17], off nt
	v_lshl_add_u64 v[16:17], v[16:17], 0, s[90:91]
	s_waitcnt vmcnt(21)
	v_cvt_pk_bf16_f32 v110, v110, v111
	v_cvt_pk_bf16_f32 v111, v112, v113
	v_cvt_pk_bf16_f32 v112, v114, v115
	v_cvt_pk_bf16_f32 v113, v116, v117
	global_store_dwordx4 v[18:19], v[110:113], off
	v_lshl_add_u64 v[18:19], v[18:19], 0, s[92:93]
	s_nop 0
	global_load_dwordx4 v[110:113], v[16:17], off offset:-16 nt
	global_load_dwordx4 v[114:117], v[16:17], off nt
	v_lshl_add_u64 v[16:17], v[16:17], 0, s[90:91]
	s_waitcnt vmcnt(21)
	v_cvt_pk_bf16_f32 v24, v24, v25
	v_cvt_pk_bf16_f32 v25, v26, v27
	v_cvt_pk_bf16_f32 v26, v28, v29
	v_cvt_pk_bf16_f32 v27, v30, v31
	global_store_dwordx4 v[18:19], v[24:27], off
	v_lshl_add_u64 v[18:19], v[18:19], 0, s[92:93]
	s_waitcnt vmcnt(19)
	v_cvt_pk_bf16_f32 v138, v138, v139
	v_cvt_pk_bf16_f32 v139, v140, v141
	v_cvt_pk_bf16_f32 v140, v142, v143
	v_cvt_pk_bf16_f32 v141, v144, v145
	global_store_dwordx4 v[18:19], v[138:141], off
	v_lshl_add_u64 v[18:19], v[18:19], 0, s[92:93]
	s_waitcnt vmcnt(17)
	v_cvt_pk_bf16_f32 v146, v146, v147
	v_cvt_pk_bf16_f32 v147, v148, v149
	v_cvt_pk_bf16_f32 v148, v150, v151
	v_cvt_pk_bf16_f32 v149, v152, v153
	global_store_dwordx4 v[18:19], v[146:149], off
	v_lshl_add_u64 v[18:19], v[18:19], 0, s[92:93]
	s_waitcnt vmcnt(15)
	v_cvt_pk_bf16_f32 v154, v154, v155
	v_cvt_pk_bf16_f32 v155, v156, v157
	v_cvt_pk_bf16_f32 v156, v158, v159
	v_cvt_pk_bf16_f32 v157, v160, v161
	global_store_dwordx4 v[18:19], v[154:157], off
	v_lshl_add_u64 v[18:19], v[18:19], 0, s[92:93]
	s_waitcnt vmcnt(13)
	v_cvt_pk_bf16_f32 v162, v162, v163
	v_cvt_pk_bf16_f32 v163, v164, v165
	v_cvt_pk_bf16_f32 v164, v194, v195
	v_cvt_pk_bf16_f32 v165, v196, v197
	global_store_dwordx4 v[18:19], v[162:165], off
	v_lshl_add_u64 v[18:19], v[18:19], 0, s[92:93]
	s_waitcnt vmcnt(11)
	v_cvt_pk_bf16_f32 v198, v198, v199
	v_cvt_pk_bf16_f32 v199, v200, v201
	v_cvt_pk_bf16_f32 v200, v202, v203
	v_cvt_pk_bf16_f32 v201, v204, v205
	global_store_dwordx4 v[18:19], v[198:201], off
	v_lshl_add_u64 v[18:19], v[18:19], 0, s[92:93]
	s_waitcnt vmcnt(9)
	v_cvt_pk_bf16_f32 v206, v206, v207
	v_cvt_pk_bf16_f32 v207, v208, v209
	v_cvt_pk_bf16_f32 v208, v210, v211
	v_cvt_pk_bf16_f32 v209, v212, v213
	global_store_dwordx4 v[18:19], v[206:209], off
	v_lshl_add_u64 v[18:19], v[18:19], 0, s[92:93]
	s_waitcnt vmcnt(7)
	v_cvt_pk_bf16_f32 v110, v110, v111
	v_cvt_pk_bf16_f32 v111, v112, v113
	v_cvt_pk_bf16_f32 v112, v114, v115
	v_cvt_pk_bf16_f32 v113, v116, v117
	global_store_dwordx4 v[18:19], v[110:113], off
	v_lshl_add_u64 v[18:19], v[18:19], 0, s[92:93]
	s_branch .LBB0_77

.LBB0_96:
	v_cvt_f32_u32_e32 v0, s28
	s_sub_i32 s38, 0, s28
	s_abs_i32 s19, s35
	s_ashr_i32 s18, s35, 31
	v_rcp_iflag_f32_e32 v0, v0
	v_mov_b32_e32 v18, v230
	v_mov_b32_e32 v2, 0
	v_mul_f32_e32 v0, 0x4f7ffffe, v0
	v_cvt_u32_f32_e32 v0, v0
	v_lshlrev_b32_e32 v1, 2, v18
	v_and_b32_e32 v1, 0xfc, v1
	v_lshlrev_b32_e32 v6, 2, v1
	v_readfirstlane_b32 vcc_lo, v0
	s_mul_i32 s38, s38, vcc_lo
	s_mul_hi_u32 s38, vcc_lo, s38
	s_add_i32 vcc_lo, vcc_lo, s38
	s_mul_hi_u32 s38, s19, vcc_lo
	s_mul_i32 vcc_lo, s38, s28
	s_sub_i32 s19, s19, vcc_lo
	s_add_i32 vcc_hi, s38, 1
	s_sub_i32 vcc_lo, s19, s28
	s_cmp_ge_u32 s19, s28
	s_cselect_b32 s38, vcc_hi, s38
	s_cselect_b32 s19, vcc_lo, s19
	s_add_i32 vcc_lo, s38, 1
	s_cmp_ge_u32 s19, s28
	s_cselect_b32 s19, vcc_lo, s38
	s_xor_b32 s19, s19, s18
	s_sub_i32 s18, s19, s18
	s_mul_i32 s19, s18, s28
	s_lshl_b32 s28, s18, 6
	s_sub_i32 s18, s35, s19
	s_lshl_b32 s35, s18, 8
	s_add_i32 s18, s35, s37
	s_ashr_i32 s19, s18, 31
	s_lshl_b64 s[18:19], s[18:19], 2
	s_add_u32 s18, s30, s18
	s_addc_u32 s19, s31, s19
	v_ashrrev_i32_e32 v19, 6, v18
	v_cmp_gt_u32_e32 vcc, s36, v1
	v_lshl_add_u64 v[16:17], s[18:19], 0, v[6:7]
	v_mov_b32_e32 v136, 0
	v_mov_b32_e32 v137, 0
	v_mov_b32_e32 v138, 0
	v_mov_b32_e32 v139, 0
	v_mov_b32_e32 v140, 0
	v_mov_b32_e32 v141, 0
	v_mov_b32_e32 v142, 0
	v_mov_b32_e32 v143, 0
	v_mov_b32_e32 v144, 0
	v_mov_b32_e32 v145, 0
	v_mov_b32_e32 v146, 0
	v_mov_b32_e32 v147, 0
	v_mov_b32_e32 v148, 0
	v_mov_b32_e32 v149, 0
	v_mov_b32_e32 v150, 0
	v_mov_b32_e32 v151, 0
	v_mov_b32_e32 v152, 0
	v_mov_b32_e32 v153, 0
	v_mov_b32_e32 v154, 0
	v_mov_b32_e32 v155, 0
	v_mov_b32_e32 v156, 0
	v_mov_b32_e32 v157, 0
	v_mov_b32_e32 v158, 0
	v_mov_b32_e32 v159, 0
	v_mov_b32_e32 v160, 0
	v_mov_b32_e32 v161, 0
	v_mov_b32_e32 v162, 0
	v_mov_b32_e32 v163, 0
	v_mov_b32_e32 v164, 0
	v_mov_b32_e32 v165, 0
	v_mov_b32_e32 v166, 0
	v_mov_b32_e32 v167, 0
	s_lshl_b64 s[100:101], s[26:27], 5
	s_and_saveexec_b64 s[18:19], vcc
	s_cbranch_execz .LconvP0_skip
	v_add_u32_e32 v2, s28, v19
	v_ashrrev_i32_e32 v3, 31, v2
	v_mul_lo_u32 v4, s26, v3
	v_mul_lo_u32 v5, s27, v2
	v_mad_u64_u32 v[2:3], s[30:31], s26, v2, 0
	v_add3_u32 v3, v3, v4, v5
	v_lshl_add_u64 v[2:3], v[2:3], 2, v[16:17]
	global_load_dwordx4 v[136:139], v[2:3], off nt
	v_lshl_add_u64 v[2:3], v[2:3], 0, s[100:101]
	global_load_dwordx4 v[140:143], v[2:3], off nt
	v_lshl_add_u64 v[2:3], v[2:3], 0, s[100:101]
	global_load_dwordx4 v[144:147], v[2:3], off nt
	v_lshl_add_u64 v[2:3], v[2:3], 0, s[100:101]
	global_load_dwordx4 v[148:151], v[2:3], off nt
	v_lshl_add_u64 v[2:3], v[2:3], 0, s[100:101]
	global_load_dwordx4 v[152:155], v[2:3], off nt
	v_lshl_add_u64 v[2:3], v[2:3], 0, s[100:101]
	global_load_dwordx4 v[156:159], v[2:3], off nt
	v_lshl_add_u64 v[2:3], v[2:3], 0, s[100:101]
	global_load_dwordx4 v[160:163], v[2:3], off nt
	v_lshl_add_u64 v[2:3], v[2:3], 0, s[100:101]
	global_load_dwordx4 v[164:167], v[2:3], off nt

.LBB0_491:
	v_cvt_f32_u32_e32 v0, s14
	s_sub_i32 s28, 0, s14
	s_abs_i32 s19, s11
	s_ashr_i32 s18, s11, 31
	v_rcp_iflag_f32_e32 v0, v0
	v_mov_b32_e32 v8, v230
	v_mov_b32_e32 v2, 0
	v_mul_f32_e32 v0, 0x4f7ffffe, v0
	v_cvt_u32_f32_e32 v0, v0
	v_lshlrev_b32_e32 v1, 2, v8
	v_and_b32_e32 v1, 0xfc, v1
	v_cmp_gt_u32_e32 vcc, s15, v1
	v_readfirstlane_b32 s29, v0
	s_mul_i32 s28, s28, s29
	s_mul_hi_u32 s28, s29, s28
	s_add_i32 s29, s29, s28
	s_mul_hi_u32 s28, s19, s29
	s_mul_i32 s29, s28, s14
	s_sub_i32 s19, s19, s29
	s_add_i32 s33, s28, 1
	s_sub_i32 s29, s19, s14
	s_cmp_ge_u32 s19, s14
	s_cselect_b32 s28, s33, s28
	s_cselect_b32 s19, s29, s19
	s_add_i32 s29, s28, 1
	s_cmp_ge_u32 s19, s14
	s_cselect_b32 s19, s29, s28
	s_xor_b32 s19, s19, s18
	s_sub_i32 s18, s19, s18
	s_mul_i32 s14, s18, s14
	s_sub_i32 s11, s11, s14
	s_lshl_b32 s11, s11, 8
	s_add_i32 s56, s11, s17
	s_ashr_i32 s57, s56, 31
	s_lshl_b32 s58, s18, 6
	s_lshl_b64 s[14:15], s[56:57], 2
	s_add_u32 s14, s36, s14
	s_addc_u32 s15, s37, s15
	v_lshlrev_b32_e32 v128, 2, v1
	v_ashrrev_i32_e32 v9, 6, v8
	v_lshl_add_u64 v[6:7], s[14:15], 0, v[128:129]
	v_mov_b32_e32 v136, 0
	v_mov_b32_e32 v137, 0
	v_mov_b32_e32 v138, 0
	v_mov_b32_e32 v139, 0
	v_mov_b32_e32 v140, 0
	v_mov_b32_e32 v141, 0
	v_mov_b32_e32 v142, 0
	v_mov_b32_e32 v143, 0
	v_mov_b32_e32 v144, 0
	v_mov_b32_e32 v145, 0
	v_mov_b32_e32 v146, 0
	v_mov_b32_e32 v147, 0
	v_mov_b32_e32 v148, 0
	v_mov_b32_e32 v149, 0
	v_mov_b32_e32 v150, 0
	v_mov_b32_e32 v151, 0
	v_mov_b32_e32 v152, 0
	v_mov_b32_e32 v153, 0
	v_mov_b32_e32 v154, 0
	v_mov_b32_e32 v155, 0
	v_mov_b32_e32 v156, 0
	v_mov_b32_e32 v157, 0
	v_mov_b32_e32 v158, 0
	v_mov_b32_e32 v159, 0
	v_mov_b32_e32 v160, 0
	v_mov_b32_e32 v161, 0
	v_mov_b32_e32 v162, 0
	v_mov_b32_e32 v163, 0
	v_mov_b32_e32 v164, 0
	v_mov_b32_e32 v165, 0
	v_mov_b32_e32 v166, 0
	v_mov_b32_e32 v167, 0
	s_lshl_b64 s[100:101], s[26:27], 5
	s_and_saveexec_b64 s[36:37], vcc
	s_cbranch_execz .LconvA_skip
	v_add_u32_e32 v2, s58, v9
	v_ashrrev_i32_e32 v3, 31, v2
	v_mul_lo_u32 v4, s26, v3
	v_mul_lo_u32 v5, s27, v2
	v_mad_u64_u32 v[2:3], s[14:15], s26, v2, 0
	v_add3_u32 v3, v3, v4, v5
	v_lshl_add_u64 v[2:3], v[2:3], 2, v[6:7]
	global_load_dwordx4 v[136:139], v[2:3], off nt
	v_lshl_add_u64 v[2:3], v[2:3], 0, s[100:101]
	global_load_dwordx4 v[140:143], v[2:3], off nt
	v_lshl_add_u64 v[2:3], v[2:3], 0, s[100:101]
	global_load_dwordx4 v[144:147], v[2:3], off nt
	v_lshl_add_u64 v[2:3], v[2:3], 0, s[100:101]
	global_load_dwordx4 v[148:151], v[2:3], off nt
	v_lshl_add_u64 v[2:3], v[2:3], 0, s[100:101]
	global_load_dwordx4 v[152:155], v[2:3], off nt
	v_lshl_add_u64 v[2:3], v[2:3], 0, s[100:101]
	global_load_dwordx4 v[156:159], v[2:3], off nt
	v_lshl_add_u64 v[2:3], v[2:3], 0, s[100:101]
	global_load_dwordx4 v[160:163], v[2:3], off nt
	v_lshl_add_u64 v[2:3], v[2:3], 0, s[100:101]
	global_load_dwordx4 v[164:167], v[2:3], off nt

.LBB0_541:
	v_cvt_f32_u32_e32 v0, s13
	s_sub_i32 s19, 0, s13
	s_abs_i32 s18, s11
	s_ashr_i32 s7, s11, 31
	v_rcp_iflag_f32_e32 v0, v0
	v_mov_b32_e32 v8, v230
	v_mov_b32_e32 v2, 0
	v_mul_f32_e32 v0, 0x4f7ffffe, v0
	v_cvt_u32_f32_e32 v0, v0
	v_lshlrev_b32_e32 v1, 2, v8
	v_and_b32_e32 v1, 0xfc, v1
	v_lshlrev_b32_e32 v128, 2, v1
	v_readfirstlane_b32 s28, v0
	s_mul_i32 s19, s19, s28
	s_mul_hi_u32 s19, s28, s19
	s_add_i32 s28, s28, s19
	s_mul_hi_u32 s19, s18, s28
	s_mul_i32 s28, s19, s13
	s_sub_i32 s18, s18, s28
	s_add_i32 s29, s19, 1
	s_sub_i32 s28, s18, s13
	s_cmp_ge_u32 s18, s13
	s_cselect_b32 s19, s29, s19
	s_cselect_b32 s18, s28, s18
	s_add_i32 s28, s19, 1
	s_cmp_ge_u32 s18, s13
	s_cselect_b32 s18, s28, s19
	s_xor_b32 s18, s18, s7
	s_sub_i32 s7, s18, s7
	s_mul_i32 s13, s7, s13
	s_lshl_b32 s56, s7, 6
	s_sub_i32 s7, s11, s13
	s_lshl_b32 s7, s7, 8
	s_add_i32 s36, s7, s17
	s_ashr_i32 s37, s36, 31
	s_lshl_b64 s[18:19], s[36:37], 2
	s_add_u32 s18, s26, s18
	s_addc_u32 s19, s27, s19
	v_ashrrev_i32_e32 v9, 6, v8
	v_cmp_gt_u32_e32 vcc, s15, v1
	v_lshl_add_u64 v[6:7], s[18:19], 0, v[128:129]
	v_mov_b32_e32 v136, 0
	v_mov_b32_e32 v137, 0
	v_mov_b32_e32 v138, 0
	v_mov_b32_e32 v139, 0
	v_mov_b32_e32 v140, 0
	v_mov_b32_e32 v141, 0
	v_mov_b32_e32 v142, 0
	v_mov_b32_e32 v143, 0
	v_mov_b32_e32 v144, 0
	v_mov_b32_e32 v145, 0
	v_mov_b32_e32 v146, 0
	v_mov_b32_e32 v147, 0
	v_mov_b32_e32 v148, 0
	v_mov_b32_e32 v149, 0
	v_mov_b32_e32 v150, 0
	v_mov_b32_e32 v151, 0
	v_mov_b32_e32 v152, 0
	v_mov_b32_e32 v153, 0
	v_mov_b32_e32 v154, 0
	v_mov_b32_e32 v155, 0
	v_mov_b32_e32 v156, 0
	v_mov_b32_e32 v157, 0
	v_mov_b32_e32 v158, 0
	v_mov_b32_e32 v159, 0
	v_mov_b32_e32 v160, 0
	v_mov_b32_e32 v161, 0
	v_mov_b32_e32 v162, 0
	v_mov_b32_e32 v163, 0
	v_mov_b32_e32 v164, 0
	v_mov_b32_e32 v165, 0
	v_mov_b32_e32 v166, 0
	v_mov_b32_e32 v167, 0
	s_lshl_b64 s[100:101], s[24:25], 5
	s_and_saveexec_b64 s[26:27], vcc
	s_cbranch_execz .LconvB_skip
	v_add_u32_e32 v2, s56, v9
	v_ashrrev_i32_e32 v3, 31, v2
	v_mul_lo_u32 v4, s24, v3
	v_mul_lo_u32 v5, s25, v2
	v_mad_u64_u32 v[2:3], s[18:19], s24, v2, 0
	v_add3_u32 v3, v3, v4, v5
	v_lshl_add_u64 v[2:3], v[2:3], 2, v[6:7]
	global_load_dwordx4 v[136:139], v[2:3], off nt
	v_lshl_add_u64 v[2:3], v[2:3], 0, s[100:101]
	global_load_dwordx4 v[140:143], v[2:3], off nt
	v_lshl_add_u64 v[2:3], v[2:3], 0, s[100:101]
	global_load_dwordx4 v[144:147], v[2:3], off nt
	v_lshl_add_u64 v[2:3], v[2:3], 0, s[100:101]
	global_load_dwordx4 v[148:151], v[2:3], off nt
	v_lshl_add_u64 v[2:3], v[2:3], 0, s[100:101]
	global_load_dwordx4 v[152:155], v[2:3], off nt
	v_lshl_add_u64 v[2:3], v[2:3], 0, s[100:101]
	global_load_dwordx4 v[156:159], v[2:3], off nt
	v_lshl_add_u64 v[2:3], v[2:3], 0, s[100:101]
	global_load_dwordx4 v[160:163], v[2:3], off nt
	v_lshl_add_u64 v[2:3], v[2:3], 0, s[100:101]
	global_load_dwordx4 v[164:167], v[2:3], off nt
